# attention loop: loop edge rotated, next iteration's staging addresses formed before the barrier instead of after it
# speedup vs baseline: 1.0018x; 1.0018x over previous
; #define LAS __attribute__((address_space(3)))
; template <bool SHIFT> DI void attn_unit(LAS unsigned char* lds, const bf16_t* Qb, const bf16_t* Kb, const bf16_t* Vt, bf16_t* concat,
;                   int b, int h, int qt, float shift2, float lam, int lam_init_bits, const float* subln_g) {
;     ...
;     for (int kt = 0; kt < nkt; ++kt) {
;         const int cur = kt & 1, nx = cur ^ 1;
;         const int vnx = vcur == 2 ? 0 : vcur + 1;
;         const bool pf = (kt + 1 < nkt);
;         const size_t ko = (size_t)(kt + 1) * 64;
;         if (pf) { *(LAS u32x4*)(lds + K_OFF + nx * K_BYTES + krow0 * QP + kc * 16) = sg0; *(LAS u32x4*)(lds + K_OFF + nx * K_BYTES + (krow0 + 32) * QP + kc * 16) = sg1;
;             sg0 = *(const u32x4*)(vg + (size_t)(vrow0) * TPB + ko + vc * 8); sg1 = *(const u32x4*)(vg + (size_t)(vrow0 + 64) * TPB + ko + vc * 8); }
;         const LAS unsigned char* kb = lds + K_OFF + cur * K_BYTES + r * QP + hh * 16;
;         const LAS unsigned char* vb = lds + V_OFF + vcur * V_BYTES + r * VP + hh * 16;
; #pragma unroll
;         for (int half = 0; half < 2; ++half) {
;             if (lag) PVH(Pc, vold);
;             QKEXP(Pc, half);
;             if (half == 0 && pf) { *(LAS u32x4*)(lds + V_OFF + vnx * V_BYTES + vrow0 * VP + vc * 16) = sg0; *(LAS u32x4*)(lds + V_OFF + vnx * V_BYTES + (vrow0 + 64) * VP + vc * 16) = sg1;
.LBB0_533:
	s_andn2_b64 s[4:5], exec, s[18:19]
	s_andn2_b64 s[6:7], exec, s[20:21]
	s_mov_b32 s65, s40
	s_and_b32 vcc_lo, s34, 1
	s_xor_b32 vcc_hi, vcc_lo, 1
	s_mulk_i32 vcc_hi, 0x4400
	s_add_i32 vcc_hi, vcc_hi, 0x11000
	v_add3_u32 v137, vcc_hi, v210, v160
	v_add3_u32 v142, vcc_hi, v214, v160
	s_mulk_i32 vcc_lo, 0x4400
	v_add_u32_e32 v254, vcc_lo, v212
	s_add_i32 vcc_lo, s65, 1
	s_cmp_lg_u32 s65, 2
	s_cselect_b32 vcc_lo, vcc_lo, 0
	s_mul_i32 vcc_lo, vcc_lo, 0x4800
	s_add_i32 vcc_lo, vcc_lo, 0x19800
	v_add3_u32 v218, vcc_lo, v215, v176
	v_add3_u32 v219, vcc_lo, v216, v176
	v_add_co_u32_e32 v138, vcc, 0xffef8000, v168
	s_nop 1
	v_addc_co_u32_e32 v139, vcc, -1, v169, vcc
.Lattn_loop:
	s_mul_i32 vcc_lo, s40, 0x4800
	v_add_u32_e32 v217, vcc_lo, v213
	ds_read_b128 v[178:181], v254
	ds_read_b128 v[186:189], v211
	ds_read_b128 v[182:185], v254 offset:32
	ds_read_b128 v[190:193], v211 offset:32
	ds_read_b128 v[228:231], v136
	ds_read_b128 v[232:235], v136 offset:4608
	s_add_i32 vcc_lo, s40, 1
	s_cmp_lg_u32 s40, 2
	s_cselect_b32 s65, vcc_lo, 0
	s_mul_i32 s37, s65, 0x4800
	s_waitcnt vmcnt(0)
	ds_write_b128 v137, v[144:147]
	ds_write_b128 v142, v[148:151]
	global_load_dwordx4 v[144:147], v[138:139], off
	global_load_dwordx4 v[148:151], v[168:169], off
	s_waitcnt lgkmcnt(6)
	v_mfma_f32_32x32x16_bf16 v[238:253], v[178:181], v[186:189], 0
	ds_read_b128 v[178:181], v254 offset:64
	ds_read_b128 v[186:189], v211 offset:64
	s_waitcnt lgkmcnt(6)
	v_mfma_f32_32x32x16_bf16 v[238:253], v[182:185], v[190:193], v[238:253]
	ds_read_b128 v[182:185], v254 offset:96
	ds_read_b128 v[190:193], v211 offset:96
	s_waitcnt lgkmcnt(2)
	v_mfma_f32_32x32x16_bf16 v[238:253], v[178:181], v[186:189], v[238:253]
	ds_read_b128 v[178:181], v254 offset:128
	ds_read_b128 v[186:189], v211 offset:128
	s_waitcnt lgkmcnt(2)
	v_mfma_f32_32x32x16_bf16 v[238:253], v[182:185], v[190:193], v[238:253]
	ds_read_b128 v[182:185], v254 offset:160
	ds_read_b128 v[190:193], v211 offset:160
	v_mfma_f32_32x32x16_bf16 v[112:127], v[228:231], v[156:159], v[112:127]
	v_mfma_f32_32x32x16_bf16 v[96:111], v[228:231], v[132:135], v[96:111]
	ds_read_b128 v[228:231], v136 offset:9216
	s_nop 7
	v_mfma_f32_32x32x16_bf16 v[80:95], v[232:235], v[156:159], v[80:95]
	v_exp_f32_e32 v238, v238
	v_exp_f32_e32 v239, v239
	v_exp_f32_e32 v240, v240
	v_exp_f32_e32 v241, v241
	v_add_f32_e32 v174, v238, v239
	v_add_f32_e32 v175, v240, v241
	v_cvt_pk_bf16_f32 v194, v238, v239
	v_mfma_f32_32x32x16_bf16 v[64:79], v[232:235], v[132:135], v[64:79]
	ds_read_b128 v[232:235], v136 offset:13824
	v_cvt_pk_bf16_f32 v195, v240, v241
	v_exp_f32_e32 v242, v242
	v_exp_f32_e32 v243, v243
	v_exp_f32_e32 v244, v244
	v_exp_f32_e32 v245, v245
	v_add_f32_e32 v174, v174, v242
	v_add_f32_e32 v175, v175, v243
	s_waitcnt lgkmcnt(1)
	v_mfma_f32_32x32x16_bf16 v[32:47], v[228:231], v[156:159], v[32:47]
	v_add_f32_e32 v174, v174, v244
	v_add_f32_e32 v175, v175, v245
	v_cvt_pk_bf16_f32 v196, v242, v243
	v_cvt_pk_bf16_f32 v197, v244, v245
	v_exp_f32_e32 v246, v246
	v_exp_f32_e32 v247, v247
	v_exp_f32_e32 v248, v248
	v_mfma_f32_32x32x16_bf16 v[48:63], v[228:231], v[132:135], v[48:63]
	ds_read_b128 v[228:231], v136 offset:32
	v_exp_f32_e32 v249, v249
	v_add_f32_e32 v174, v174, v246
	v_add_f32_e32 v175, v175, v247
	v_add_f32_e32 v174, v174, v248
	v_add_f32_e32 v175, v175, v249
	v_cvt_pk_bf16_f32 v198, v246, v247
	v_cvt_pk_bf16_f32 v199, v248, v249
	s_waitcnt lgkmcnt(1)
	v_mfma_f32_32x32x16_bf16 v[16:31], v[232:235], v[156:159], v[16:31]
	v_exp_f32_e32 v250, v250
	v_exp_f32_e32 v251, v251
	v_exp_f32_e32 v252, v252
	v_exp_f32_e32 v253, v253
	v_add_f32_e32 v174, v174, v250
	v_add_f32_e32 v175, v175, v251
	v_mfma_f32_32x32x16_bf16 v[0:15], v[232:235], v[132:135], v[0:15]
	ds_read_b128 v[232:235], v136 offset:4640
	v_add_f32_e32 v174, v174, v252
	v_add_f32_e32 v175, v175, v253
	v_cvt_pk_bf16_f32 v200, v250, v251
	v_cvt_pk_bf16_f32 v201, v252, v253
	v_add_f32_e32 v174, v174, v175
	v_add_f32_e32 v165, v165, v174
	v_mfma_f32_32x32x16_bf16 v[238:253], v[178:181], v[186:189], 0
	ds_read_b128 v[178:181], v254 offset:192
	ds_read_b128 v[186:189], v211 offset:192
	v_mfma_f32_32x32x16_bf16 v[238:253], v[182:185], v[190:193], v[238:253]
	ds_read_b128 v[182:185], v254 offset:224
	ds_read_b128 v[190:193], v211 offset:224
	s_waitcnt lgkmcnt(2)
	v_mfma_f32_32x32x16_bf16 v[238:253], v[178:181], v[186:189], v[238:253]
	ds_read_b128 v[178:181], v254 offset:8704
	ds_read_b128 v[186:189], v211
	s_waitcnt lgkmcnt(2)
	v_mfma_f32_32x32x16_bf16 v[238:253], v[182:185], v[190:193], v[238:253]
	ds_read_b128 v[182:185], v254 offset:8736
	ds_read_b128 v[190:193], v211 offset:32
	v_mfma_f32_32x32x16_bf16 v[112:127], v[228:231], v[152:155], v[112:127]
	v_mfma_f32_32x32x16_bf16 v[96:111], v[228:231], v[128:131], v[96:111]
	ds_read_b128 v[228:231], v136 offset:9248
	s_nop 7
	v_mfma_f32_32x32x16_bf16 v[80:95], v[232:235], v[152:155], v[80:95]
	v_exp_f32_e32 v238, v238
	v_exp_f32_e32 v239, v239
	v_exp_f32_e32 v240, v240
	v_exp_f32_e32 v241, v241
	v_add_f32_e32 v174, v238, v239
	v_add_f32_e32 v175, v240, v241
	v_cvt_pk_bf16_f32 v202, v238, v239
	v_mfma_f32_32x32x16_bf16 v[64:79], v[232:235], v[128:131], v[64:79]
	ds_read_b128 v[232:235], v136 offset:13856
	v_cvt_pk_bf16_f32 v203, v240, v241
	v_exp_f32_e32 v242, v242
	v_exp_f32_e32 v243, v243
	v_exp_f32_e32 v244, v244
	v_exp_f32_e32 v245, v245
	v_add_f32_e32 v174, v174, v242
	v_add_f32_e32 v175, v175, v243
	s_waitcnt lgkmcnt(1)
	v_mfma_f32_32x32x16_bf16 v[32:47], v[228:231], v[152:155], v[32:47]
	v_add_f32_e32 v174, v174, v244
	v_add_f32_e32 v175, v175, v245
	v_cvt_pk_bf16_f32 v204, v242, v243
	v_cvt_pk_bf16_f32 v205, v244, v245
	v_exp_f32_e32 v246, v246
	v_exp_f32_e32 v247, v247
	v_exp_f32_e32 v248, v248
	v_mfma_f32_32x32x16_bf16 v[48:63], v[228:231], v[128:131], v[48:63]
	ds_read_b128 v[228:231], v217
	v_exp_f32_e32 v249, v249
	v_add_f32_e32 v174, v174, v246
	v_add_f32_e32 v175, v175, v247
	v_add_f32_e32 v174, v174, v248
	v_add_f32_e32 v175, v175, v249
	v_cvt_pk_bf16_f32 v206, v246, v247
	v_cvt_pk_bf16_f32 v207, v248, v249
	s_waitcnt lgkmcnt(1)
	v_mfma_f32_32x32x16_bf16 v[16:31], v[232:235], v[152:155], v[16:31]
	v_exp_f32_e32 v250, v250
	v_exp_f32_e32 v251, v251
	v_exp_f32_e32 v252, v252
	v_exp_f32_e32 v253, v253
	v_add_f32_e32 v174, v174, v250
	v_add_f32_e32 v175, v175, v251
	v_mfma_f32_32x32x16_bf16 v[0:15], v[232:235], v[128:131], v[0:15]
	ds_read_b128 v[232:235], v217 offset:4608
	v_add_f32_e32 v174, v174, v252
	v_add_f32_e32 v175, v175, v253
	v_cvt_pk_bf16_f32 v208, v250, v251
	v_cvt_pk_bf16_f32 v209, v252, v253
	v_add_f32_e32 v174, v174, v175
	v_add_f32_e32 v164, v164, v174
	s_waitcnt vmcnt(0)
	ds_write_b128 v218, v[144:147]
	ds_write_b128 v219, v[148:151]
	s_cmp_ge_u32 s34, s35
	s_cbranch_scc1 .Lattn_kskip_s
; #define LAS __attribute__((address_space(3)))
; #define SB0() __builtin_amdgcn_sched_barrier(0)
; template <bool SHIFT> DI void attn_unit(LAS unsigned char* lds, const bf16_t* Qb, const bf16_t* Kb, const bf16_t* Vt, bf16_t* concat,
;                   int b, int h, int qt, float shift2, float lam, int lam_init_bits, const float* subln_g) {
;     ...
;         for (int half = 0; half < 2; ++half) {
;             if (lag) PVH(Pc, vold);
;             QKEXP(Pc, half);
;             if (half == 0 && pf) { *(LAS u32x4*)(lds + V_OFF + vnx * V_BYTES + vrow0 * VP + vc * 16) = sg0; *(LAS u32x4*)(lds + V_OFF + vnx * V_BYTES + (vrow0 + 64) * VP + vc * 16) = sg1;
;                 if (kt + 2 < nkt) { sg0 = *(const u32x4*)(kg + (ko + 64 + krow0) * 1024 + kc * 8); sg1 = *(const u32x4*)(kg + (ko + 64 + krow0 + 32) * 1024 + kc * 8); } }
;             vold = vb + half * 64;
;             SB0();
;             if (!lag) PVH(Pc, vold);
;         }
;         __syncthreads();
;         vcur = vnx;
	v_lshl_add_u64 v[170:171], v[166:167], 0, s[22:23]
	v_add_co_u32_e32 v172, vcc, 0xc5c8000, v170
	s_nop 1
	v_addc_co_u32_e32 v173, vcc, 0, v171, vcc
	v_add_co_u32_e32 v170, vcc, 0xc5d8000, v170
	s_nop 1
	v_addc_co_u32_e32 v171, vcc, 0, v171, vcc
	global_load_dwordx4 v[144:147], v[172:173], off
	global_load_dwordx4 v[148:151], v[170:171], off
.Lattn_kskip_s:
	v_mfma_f32_32x32x16_bf16 v[238:253], v[178:181], v[186:189], 0
	ds_read_b128 v[178:181], v254 offset:8768
	ds_read_b128 v[186:189], v211 offset:64
	v_mfma_f32_32x32x16_bf16 v[238:253], v[182:185], v[190:193], v[238:253]
	ds_read_b128 v[182:185], v254 offset:8800
	ds_read_b128 v[190:193], v211 offset:96
	s_waitcnt lgkmcnt(2)
	v_mfma_f32_32x32x16_bf16 v[238:253], v[178:181], v[186:189], v[238:253]
	ds_read_b128 v[178:181], v254 offset:8832
	ds_read_b128 v[186:189], v211 offset:128
	s_waitcnt lgkmcnt(2)
	v_mfma_f32_32x32x16_bf16 v[238:253], v[182:185], v[190:193], v[238:253]
	ds_read_b128 v[182:185], v254 offset:8864
	ds_read_b128 v[190:193], v211 offset:160
	v_mfma_f32_32x32x16_bf16 v[112:127], v[228:231], v[194:197], v[112:127]
	v_mfma_f32_32x32x16_bf16 v[96:111], v[228:231], v[202:205], v[96:111]
	ds_read_b128 v[228:231], v217 offset:9216
	s_nop 7
	v_mfma_f32_32x32x16_bf16 v[80:95], v[232:235], v[194:197], v[80:95]
	v_exp_f32_e32 v238, v238
	v_exp_f32_e32 v239, v239
	v_exp_f32_e32 v240, v240
	v_exp_f32_e32 v241, v241
	v_add_f32_e32 v174, v238, v239
	v_add_f32_e32 v175, v240, v241
	v_cvt_pk_bf16_f32 v156, v238, v239
	v_mfma_f32_32x32x16_bf16 v[64:79], v[232:235], v[202:205], v[64:79]
	ds_read_b128 v[232:235], v217 offset:13824
	v_cvt_pk_bf16_f32 v157, v240, v241
	v_exp_f32_e32 v242, v242
	v_exp_f32_e32 v243, v243
	v_exp_f32_e32 v244, v244
	v_exp_f32_e32 v245, v245
	v_add_f32_e32 v174, v174, v242
	v_add_f32_e32 v175, v175, v243
	s_waitcnt lgkmcnt(1)
	v_mfma_f32_32x32x16_bf16 v[32:47], v[228:231], v[194:197], v[32:47]
	v_add_f32_e32 v174, v174, v244
	v_add_f32_e32 v175, v175, v245
	v_cvt_pk_bf16_f32 v158, v242, v243
	v_cvt_pk_bf16_f32 v159, v244, v245
	v_exp_f32_e32 v246, v246
	v_exp_f32_e32 v247, v247
	v_exp_f32_e32 v248, v248
	v_mfma_f32_32x32x16_bf16 v[48:63], v[228:231], v[202:205], v[48:63]
	ds_read_b128 v[228:231], v217 offset:32
	v_exp_f32_e32 v249, v249
	v_add_f32_e32 v174, v174, v246
	v_add_f32_e32 v175, v175, v247
	v_add_f32_e32 v174, v174, v248
	v_add_f32_e32 v175, v175, v249
	v_cvt_pk_bf16_f32 v152, v246, v247
	v_cvt_pk_bf16_f32 v153, v248, v249
	s_waitcnt lgkmcnt(1)
	v_mfma_f32_32x32x16_bf16 v[16:31], v[232:235], v[194:197], v[16:31]
	v_exp_f32_e32 v250, v250
	v_exp_f32_e32 v251, v251
	v_exp_f32_e32 v252, v252
	v_exp_f32_e32 v253, v253
	v_add_f32_e32 v174, v174, v250
	v_add_f32_e32 v175, v175, v251
	v_mfma_f32_32x32x16_bf16 v[0:15], v[232:235], v[202:205], v[0:15]
	ds_read_b128 v[232:235], v217 offset:4640
	v_add_f32_e32 v174, v174, v252
	v_add_f32_e32 v175, v175, v253
	v_cvt_pk_bf16_f32 v154, v250, v251
	v_cvt_pk_bf16_f32 v155, v252, v253
	v_add_f32_e32 v174, v174, v175
	v_add_f32_e32 v165, v165, v174
	v_mfma_f32_32x32x16_bf16 v[238:253], v[178:181], v[186:189], 0
	ds_read_b128 v[178:181], v254 offset:8896
	ds_read_b128 v[186:189], v211 offset:192
	v_mfma_f32_32x32x16_bf16 v[238:253], v[182:185], v[190:193], v[238:253]
	ds_read_b128 v[182:185], v254 offset:8928
	ds_read_b128 v[190:193], v211 offset:224
	s_waitcnt lgkmcnt(2)
	v_mfma_f32_32x32x16_bf16 v[238:253], v[178:181], v[186:189], v[238:253]
	s_waitcnt lgkmcnt(0)
	v_mfma_f32_32x32x16_bf16 v[238:253], v[182:185], v[190:193], v[238:253]
	v_mfma_f32_32x32x16_bf16 v[112:127], v[228:231], v[198:201], v[112:127]
	v_mfma_f32_32x32x16_bf16 v[96:111], v[228:231], v[206:209], v[96:111]
	ds_read_b128 v[228:231], v217 offset:9248
	s_nop 7
	v_mfma_f32_32x32x16_bf16 v[80:95], v[232:235], v[198:201], v[80:95]
	v_exp_f32_e32 v238, v238
	v_exp_f32_e32 v239, v239
	v_exp_f32_e32 v240, v240
	v_exp_f32_e32 v241, v241
	v_add_f32_e32 v174, v238, v239
	v_add_f32_e32 v175, v240, v241
	v_cvt_pk_bf16_f32 v132, v238, v239
	v_mfma_f32_32x32x16_bf16 v[64:79], v[232:235], v[206:209], v[64:79]
	ds_read_b128 v[232:235], v217 offset:13856
	v_cvt_pk_bf16_f32 v133, v240, v241
	v_exp_f32_e32 v242, v242
	v_exp_f32_e32 v243, v243
	v_exp_f32_e32 v244, v244
	v_exp_f32_e32 v245, v245
	v_add_f32_e32 v174, v174, v242
	v_add_f32_e32 v175, v175, v243
	s_waitcnt lgkmcnt(1)
	v_mfma_f32_32x32x16_bf16 v[32:47], v[228:231], v[198:201], v[32:47]
	v_add_f32_e32 v174, v174, v244
	v_add_f32_e32 v175, v175, v245
	v_cvt_pk_bf16_f32 v134, v242, v243
	v_cvt_pk_bf16_f32 v135, v244, v245
	v_exp_f32_e32 v246, v246
	v_exp_f32_e32 v247, v247
	v_exp_f32_e32 v248, v248
	v_mfma_f32_32x32x16_bf16 v[48:63], v[228:231], v[206:209], v[48:63]
	v_exp_f32_e32 v249, v249
	v_add_f32_e32 v174, v174, v246
	v_add_f32_e32 v175, v175, v247
	v_add_f32_e32 v174, v174, v248
	v_add_f32_e32 v175, v175, v249
	v_cvt_pk_bf16_f32 v128, v246, v247
	v_cvt_pk_bf16_f32 v129, v248, v249
	s_waitcnt lgkmcnt(0)
	v_mfma_f32_32x32x16_bf16 v[16:31], v[232:235], v[198:201], v[16:31]
	v_exp_f32_e32 v250, v250
	v_exp_f32_e32 v251, v251
	v_exp_f32_e32 v252, v252
	v_exp_f32_e32 v253, v253
	v_add_f32_e32 v174, v174, v250
	v_add_f32_e32 v175, v175, v251
	v_mfma_f32_32x32x16_bf16 v[0:15], v[232:235], v[206:209], v[0:15]
	v_add_f32_e32 v174, v174, v252
	v_add_f32_e32 v175, v175, v253
	v_cvt_pk_bf16_f32 v130, v250, v251
	v_cvt_pk_bf16_f32 v131, v252, v253
	v_add_f32_e32 v174, v174, v175
	v_add_f32_e32 v164, v164, v174
	s_add_u32 s22, s22, 0x20000
	s_addc_u32 s23, s23, 0
	s_add_i32 s34, s34, 1
	v_add_u32_e32 v136, 64, v217
	v_lshl_add_u64 v[168:169], v[168:169], 0, s[56:57]
	s_and_b32 vcc_lo, s34, 1
	s_xor_b32 vcc_hi, vcc_lo, 1
	s_mulk_i32 vcc_hi, 0x4400
	s_add_i32 vcc_hi, vcc_hi, 0x11000
	v_add3_u32 v137, vcc_hi, v210, v160
	v_add3_u32 v142, vcc_hi, v214, v160
	s_mulk_i32 vcc_lo, 0x4400
	v_add_u32_e32 v254, vcc_lo, v212
	s_add_i32 vcc_lo, s65, 1
	s_cmp_lg_u32 s65, 2
	s_cselect_b32 vcc_lo, vcc_lo, 0
	s_mul_i32 vcc_lo, vcc_lo, 0x4800
	s_add_i32 vcc_lo, vcc_lo, 0x19800
	v_add3_u32 v218, vcc_lo, v215, v176
	v_add3_u32 v219, vcc_lo, v216, v176
	v_add_co_u32_e32 v138, vcc, 0xffef8000, v168
	s_nop 1
	v_addc_co_u32_e32 v139, vcc, -1, v169, vcc
	s_waitcnt lgkmcnt(0)
	s_cmp_eq_u32 s36, s22
	s_barrier
	s_cbranch_scc1 .LBB0_545
	s_mov_b32 s40, s65
	s_branch .Lattn_loop
